# v_combo12 + p6a_prep unit order head-fastest (all 8 heads of a row block processed at the same time: full 2 KB rows per DRAM page)
# baseline (speedup 1.0000x reference)
.LBB0_552:
	s_bfe_u32 s50, s48, 0x30000
	s_lshl_b32 s51, s50, 7
	v_readlane_b32 s76, v247, 26
	v_or_b32_e32 v0, s51, v20
	v_readlane_b32 s82, v247, 32
	v_readlane_b32 s83, v247, 33
	v_lshlrev_b32_e32 v22, 2, v0
	s_mov_b64 s[54:55], s[82:83]
	v_lshl_add_u64 v[0:1], s[54:55], 0, v[22:23]
	s_ashr_i32 s42, s48, 10
	v_add_co_u32_e32 v0, vcc, 0x1000, v0
	s_bfe_u32 s49, s48, 0x70003
	s_nop 0
	v_addc_co_u32_e32 v1, vcc, 0, v1, vcc
	s_ashr_i32 s43, s42, 31
	global_load_dwordx2 v[0:1], v[0:1], off
	s_nop 0
	global_load_dwordx2 v[2:3], v22, s[82:83]
	s_lshl_b64 s[44:45], s[42:43], 23
	v_lshl_add_u32 v22, s49, 16, v94
	v_lshl_add_u64 v[4:5], s[44:45], 0, v[22:23]
	v_or_b32_e32 v4, s51, v4
	v_or_b32_e32 v4, v4, v20
	v_lshlrev_b64 v[26:27], 1, v[4:5]
	v_lshl_add_u64 v[34:35], s[34:35], 0, v[26:27]
	v_add_co_u32_e32 v4, vcc, s33, v34
	v_lshl_add_u64 v[32:33], s[36:37], 0, v[26:27]
	s_nop 0
	v_addc_co_u32_e32 v5, vcc, 0, v35, vcc
	v_add_co_u32_e32 v6, vcc, s33, v32
	v_lshl_add_u64 v[30:31], s[38:39], 0, v[26:27]
	s_nop 0
	v_addc_co_u32_e32 v7, vcc, 0, v33, vcc
	global_load_dword v16, v[32:33], off
	global_load_dword v46, v[30:31], off offset:2048
	global_load_dword v99, v[4:5], off offset:2048
	global_load_dword v17, v[6:7], off offset:2048
	global_load_dword v18, v[32:33], off offset:2048
	v_add_co_u32_e32 v4, vcc, s46, v32
	v_readlane_b32 s77, v247, 27
	s_nop 0
	v_addc_co_u32_e32 v5, vcc, 0, v33, vcc
	v_add_co_u32_e32 v6, vcc, s46, v34
	global_load_dword v19, v[4:5], off offset:-4096
	global_load_dword v28, v[4:5], off
	v_addc_co_u32_e32 v7, vcc, 0, v35, vcc
	v_add_co_u32_e32 v8, vcc, s33, v30
	v_readlane_b32 s78, v247, 28
	s_nop 0
	v_addc_co_u32_e32 v9, vcc, 0, v31, vcc
	v_add_co_u32_e32 v10, vcc, s46, v30
	v_readlane_b32 s79, v247, 29
	s_nop 0
	v_addc_co_u32_e32 v11, vcc, 0, v31, vcc
	global_load_dword v47, v[10:11], off
	global_load_dword v52, v[10:11], off offset:2048
	global_load_dword v29, v[4:5], off offset:2048
	v_add_co_u32_e32 v4, vcc, s47, v34
	v_readlane_b32 s80, v247, 30
	s_nop 0
	v_addc_co_u32_e32 v5, vcc, 0, v35, vcc
	v_add_co_u32_e32 v12, vcc, s47, v32
	v_readlane_b32 s81, v247, 31
	s_nop 0
	v_addc_co_u32_e32 v13, vcc, 0, v33, vcc
	global_load_dword v36, v[12:13], off
	v_add_co_u32_e32 v14, vcc, s47, v30
	v_readlane_b32 s84, v247, 34
	s_nop 0
	v_addc_co_u32_e32 v15, vcc, 0, v31, vcc
	global_load_dword v53, v[30:31], off
	global_load_dword v112, v[34:35], off
	global_load_dword v113, v[34:35], off offset:2048
	global_load_dword v37, v[14:15], off offset:2048
	global_load_dword v38, v[12:13], off offset:2048
	global_load_dword v54, v[10:11], off offset:-4096
	global_load_dword v100, v[6:7], off
	global_load_dword v98, v[6:7], off offset:2048
	global_load_dword v55, v[14:15], off
	global_load_dword v101, v[6:7], off offset:-4096
	global_load_dword v60, v[8:9], off offset:2048
	global_load_dword v97, v[4:5], off
	global_load_dword v22, v[4:5], off offset:2048
	v_readlane_b32 s85, v247, 35
	v_readlane_b32 s86, v247, 36
	v_readlane_b32 s87, v247, 37
	v_readlane_b32 s88, v247, 38
	v_readlane_b32 s89, v247, 39
	v_readlane_b32 s90, v247, 40
	v_readlane_b32 s91, v247, 41
	s_waitcnt vmcnt(24)
	v_sub_f32_e32 v0, v0, v2
	v_sub_f32_e32 v1, v1, v3
	v_mul_f32_e32 v0, 0x3fb8aa3b, v0
	v_mul_f32_e32 v1, 0x3fb8aa3b, v1
	v_exp_f32_e32 v0, v0
	v_exp_f32_e32 v1, v1
	s_waitcnt vmcnt(23)
	v_lshlrev_b32_e32 v2, 16, v16
	v_pk_add_f32 v[0:1], v[0:1], 1.0 op_sel_hi:[1,0]
	s_waitcnt vmcnt(19)
	v_lshlrev_b32_e32 v4, 16, v18
	v_and_b32_e32 v5, 0xffff0000, v18
	v_div_scale_f32 v18, s[44:45], v1, v1, 1.0
	v_and_b32_e32 v3, 0xffff0000, v16
	v_mul_f32_e32 v2, 0xbfb8aa3b, v2
	v_mul_f32_e32 v3, 0xbfb8aa3b, v3
	s_waitcnt vmcnt(18)
	v_lshlrev_b32_e32 v6, 16, v19
	v_and_b32_e32 v7, 0xffff0000, v19
	v_rcp_f32_e32 v19, v18
	s_waitcnt vmcnt(17)
	v_lshlrev_b32_e32 v10, 16, v28
	v_and_b32_e32 v11, 0xffff0000, v28
	v_mul_f32_e32 v4, 0xbfb8aa3b, v4
	v_fma_f32 v28, -v18, v19, 1.0
	v_fmac_f32_e32 v19, v28, v19
	v_div_scale_f32 v28, vcc, 1.0, v1, 1.0
	v_mul_f32_e32 v5, 0xbfb8aa3b, v5
	v_exp_f32_e32 v2, v2
	v_exp_f32_e32 v3, v3
	v_exp_f32_e32 v4, v4
	s_waitcnt vmcnt(14)
	v_lshlrev_b32_e32 v12, 16, v29
	v_and_b32_e32 v13, 0xffff0000, v29
	v_mul_f32_e32 v29, v28, v19
	v_exp_f32_e32 v5, v5
	v_mul_f32_e32 v6, 0xbfb8aa3b, v6
	v_mul_f32_e32 v7, 0xbfb8aa3b, v7
	v_lshlrev_b32_e32 v8, 16, v17
	v_and_b32_e32 v9, 0xffff0000, v17
	v_exp_f32_e32 v6, v6
	v_exp_f32_e32 v7, v7
	v_mul_f32_e32 v8, 0xbfb8aa3b, v8
	s_waitcnt vmcnt(13)
	v_lshlrev_b32_e32 v14, 16, v36
	v_and_b32_e32 v15, 0xffff0000, v36
	v_fma_f32 v36, -v18, v29, v28
	v_fmac_f32_e32 v29, v36, v19
	v_fma_f32 v18, -v18, v29, v28
	v_div_scale_f32 v28, s[44:45], v0, v0, 1.0
	v_rcp_f32_e32 v36, v28
	v_div_fmas_f32 v18, v18, v19, v29
	v_div_fixup_f32 v1, v18, v1, 1.0
	v_mul_f32_e32 v9, 0xbfb8aa3b, v9
	v_fma_f32 v18, -v28, v36, 1.0
	v_fmac_f32_e32 v36, v18, v36
	v_div_scale_f32 v18, vcc, 1.0, v0, 1.0
	v_exp_f32_e32 v8, v8
	v_exp_f32_e32 v9, v9
	v_mul_f32_e32 v10, 0xbfb8aa3b, v10
	v_mul_f32_e32 v11, 0xbfb8aa3b, v11
	v_mul_f32_e32 v19, v18, v36
	v_exp_f32_e32 v10, v10
	v_exp_f32_e32 v11, v11
	v_mul_f32_e32 v12, 0xbfb8aa3b, v12
	v_mul_f32_e32 v13, 0xbfb8aa3b, v13
	v_fma_f32 v29, -v28, v19, v18
	v_add_f32_e32 v2, 1.0, v2
	v_add_f32_e32 v3, 1.0, v3
	v_add_f32_e32 v4, 1.0, v4
	v_add_f32_e32 v5, 1.0, v5
	v_exp_f32_e32 v12, v12
	v_exp_f32_e32 v13, v13
	v_mul_f32_e32 v14, 0xbfb8aa3b, v14
	v_mul_f32_e32 v15, 0xbfb8aa3b, v15
	s_waitcnt vmcnt(8)
	v_lshlrev_b32_e32 v16, 16, v38
	v_and_b32_e32 v17, 0xffff0000, v38
	v_fmac_f32_e32 v19, v29, v36
	v_rcp_f32_e32 v2, v2
	v_rcp_f32_e32 v3, v3
	v_rcp_f32_e32 v4, v4
	v_rcp_f32_e32 v5, v5
	v_add_f32_e32 v6, 1.0, v6
	v_add_f32_e32 v7, 1.0, v7
	v_exp_f32_e32 v14, v14
	v_exp_f32_e32 v15, v15
	v_mul_f32_e32 v16, 0xbfb8aa3b, v16
	v_mul_f32_e32 v17, 0xbfb8aa3b, v17
	v_fma_f32 v18, -v28, v19, v18
	v_rcp_f32_e32 v6, v6
	v_rcp_f32_e32 v7, v7
	v_add_f32_e32 v8, 1.0, v8
	v_add_f32_e32 v9, 1.0, v9
	v_exp_f32_e32 v16, v16
	v_exp_f32_e32 v17, v17
	v_div_fmas_f32 v18, v18, v36, v19
	v_rcp_f32_e32 v8, v8
	v_rcp_f32_e32 v9, v9
	v_add_f32_e32 v10, 1.0, v10
	v_add_f32_e32 v11, 1.0, v11
	v_div_fixup_f32 v0, v18, v0, 1.0
	v_rcp_f32_e32 v10, v10
	v_rcp_f32_e32 v11, v11
	v_add_f32_e32 v12, 1.0, v12
	v_add_f32_e32 v13, 1.0, v13
	v_pk_add_f32 v[18:19], v[0:1], 1.0 op_sel_hi:[1,0] neg_lo:[1,0] neg_hi:[1,0]
	v_rcp_f32_e32 v12, v12
	v_rcp_f32_e32 v13, v13
	v_add_f32_e32 v14, 1.0, v14
	v_add_f32_e32 v15, 1.0, v15
	v_pk_fma_f32 v[86:87], v[18:19], v[2:3], v[0:1]
	v_pk_fma_f32 v[78:79], v[18:19], v[4:5], v[0:1]
	v_lshlrev_b32_e32 v2, 16, v37
	v_and_b32_e32 v3, 0xffff0000, v37
	s_waitcnt vmcnt(4)
	v_lshlrev_b32_e32 v4, 16, v55
	v_and_b32_e32 v5, 0xffff0000, v55
	v_rcp_f32_e32 v14, v14
	v_rcp_f32_e32 v15, v15
	v_add_f32_e32 v16, 1.0, v16
	v_add_f32_e32 v17, 1.0, v17
	v_pk_fma_f32 v[64:65], v[18:19], v[6:7], v[0:1]
	v_mul_f32_e32 v2, 0xbfb8aa3b, v2
	v_mul_f32_e32 v3, 0xbfb8aa3b, v3
	v_mul_f32_e32 v4, 0xbfb8aa3b, v4
	v_mul_f32_e32 v5, 0xbfb8aa3b, v5
	v_lshlrev_b32_e32 v6, 16, v52
	v_and_b32_e32 v7, 0xffff0000, v52
	v_rcp_f32_e32 v16, v16
	v_rcp_f32_e32 v17, v17
	v_pk_fma_f32 v[56:57], v[18:19], v[8:9], v[0:1]
	v_exp_f32_e32 v2, v2
	v_exp_f32_e32 v3, v3
	v_exp_f32_e32 v4, v4
	v_exp_f32_e32 v5, v5
	v_mul_f32_e32 v6, 0xbfb8aa3b, v6
	v_mul_f32_e32 v7, 0xbfb8aa3b, v7
	v_lshlrev_b32_e32 v8, 16, v47
	v_and_b32_e32 v9, 0xffff0000, v47
	v_pk_fma_f32 v[48:49], v[18:19], v[10:11], v[0:1]
	v_exp_f32_e32 v6, v6
	v_exp_f32_e32 v7, v7
	v_mul_f32_e32 v8, 0xbfb8aa3b, v8
	v_mul_f32_e32 v9, 0xbfb8aa3b, v9
	s_waitcnt vmcnt(2)
	v_lshlrev_b32_e32 v10, 16, v60
	v_and_b32_e32 v11, 0xffff0000, v60
	v_pk_fma_f32 v[42:43], v[18:19], v[12:13], v[0:1]
	v_exp_f32_e32 v8, v8
	v_exp_f32_e32 v9, v9
	v_mul_f32_e32 v10, 0xbfb8aa3b, v10
	v_mul_f32_e32 v11, 0xbfb8aa3b, v11
	v_lshlrev_b32_e32 v12, 16, v54
	v_and_b32_e32 v13, 0xffff0000, v54
	v_pk_fma_f32 v[38:39], v[18:19], v[14:15], v[0:1]
	v_exp_f32_e32 v10, v10
	v_exp_f32_e32 v11, v11
	v_mul_f32_e32 v12, 0xbfb8aa3b, v12
	v_mul_f32_e32 v13, 0xbfb8aa3b, v13
	v_lshlrev_b32_e32 v14, 16, v46
	v_and_b32_e32 v15, 0xffff0000, v46
	v_pk_fma_f32 v[28:29], v[18:19], v[16:17], v[0:1]
	v_add_f32_e32 v2, 1.0, v2
	v_add_f32_e32 v3, 1.0, v3
	v_add_f32_e32 v4, 1.0, v4
	v_add_f32_e32 v5, 1.0, v5
	v_exp_f32_e32 v12, v12
	v_exp_f32_e32 v13, v13
	v_mul_f32_e32 v14, 0xbfb8aa3b, v14
	v_mul_f32_e32 v15, 0xbfb8aa3b, v15
	v_lshlrev_b32_e32 v16, 16, v53
	v_and_b32_e32 v17, 0xffff0000, v53
	v_rcp_f32_e32 v2, v2
	v_rcp_f32_e32 v3, v3
	v_rcp_f32_e32 v4, v4
	v_rcp_f32_e32 v5, v5
	v_add_f32_e32 v6, 1.0, v6
	v_add_f32_e32 v7, 1.0, v7
	v_exp_f32_e32 v14, v14
	v_exp_f32_e32 v15, v15
	v_mul_f32_e32 v16, 0xbfb8aa3b, v16
	v_mul_f32_e32 v17, 0xbfb8aa3b, v17
	v_rcp_f32_e32 v6, v6
	v_rcp_f32_e32 v7, v7
	v_add_f32_e32 v8, 1.0, v8
	v_add_f32_e32 v9, 1.0, v9
	v_exp_f32_e32 v16, v16
	v_exp_f32_e32 v17, v17
	v_rcp_f32_e32 v8, v8
	v_rcp_f32_e32 v9, v9
	v_add_f32_e32 v10, 1.0, v10
	v_add_f32_e32 v11, 1.0, v11
	v_rcp_f32_e32 v10, v10
	v_rcp_f32_e32 v11, v11
	v_add_f32_e32 v12, 1.0, v12
	v_add_f32_e32 v13, 1.0, v13
	v_rcp_f32_e32 v12, v12
	v_rcp_f32_e32 v13, v13
	v_add_f32_e32 v14, 1.0, v14
	v_add_f32_e32 v15, 1.0, v15
	v_pk_fma_f32 v[46:47], v[18:19], v[2:3], v[0:1]
	v_pk_fma_f32 v[54:55], v[18:19], v[4:5], v[0:1]
	v_pk_mul_f32 v[82:83], v[86:87], v[78:79]
	v_rcp_f32_e32 v14, v14
	v_rcp_f32_e32 v15, v15
	v_add_f32_e32 v16, 1.0, v16
	v_add_f32_e32 v17, 1.0, v17
	v_pk_mul_f32 v[60:61], v[54:55], v[46:47]
	v_pk_fma_f32 v[62:63], v[18:19], v[6:7], v[0:1]
	v_pk_mul_f32 v[72:73], v[82:83], v[64:65]
	v_rcp_f32_e32 v16, v16
	v_rcp_f32_e32 v17, v17
	v_pk_mul_f32 v[76:77], v[62:63], v[60:61]
	v_pk_fma_f32 v[80:81], v[18:19], v[8:9], v[0:1]
	v_pk_mul_f32 v[58:59], v[72:73], v[56:57]
	v_pk_mul_f32 v[84:85], v[80:81], v[76:77]
	v_pk_fma_f32 v[88:89], v[18:19], v[10:11], v[0:1]
	v_pk_mul_f32 v[50:51], v[58:59], v[48:49]
	v_pk_mul_f32 v[90:91], v[88:89], v[84:85]
	v_pk_fma_f32 v[92:93], v[18:19], v[12:13], v[0:1]
	v_pk_mul_f32 v[44:45], v[50:51], v[42:43]
	v_pk_mul_f32 v[102:103], v[92:93], v[90:91]
	v_pk_fma_f32 v[104:105], v[18:19], v[14:15], v[0:1]
	v_pk_mul_f32 v[40:41], v[44:45], v[38:39]
	v_pk_mul_f32 v[106:107], v[104:105], v[102:103]
	v_pk_fma_f32 v[108:109], v[18:19], v[16:17], v[0:1]
	v_pk_mul_f32 v[36:37], v[40:41], v[28:29]
	v_pk_mul_f32 v[110:111], v[108:109], v[106:107]
	ds_write2st64_b64 v95, v[36:37], v[110:111] offset1:8
	s_waitcnt lgkmcnt(0)
	s_barrier
	ds_read2st64_b64 v[8:11], v21 offset1:1
	ds_read2st64_b64 v[12:15], v21 offset0:2 offset1:3
	ds_read2st64_b64 v[0:3], v21 offset0:9 offset1:10
	v_lshlrev_b32_e32 v118, 16, v112
	v_and_b32_e32 v112, 0xffff0000, v112
	s_waitcnt lgkmcnt(2)
	v_cndmask_b32_e64 v4, v9, 1.0, s[0:1]
	v_cndmask_b32_e64 v5, v8, 1.0, s[0:1]
	v_mul_f32_e32 v6, v5, v10
	v_mul_f32_e32 v7, v4, v11
	v_cndmask_b32_e64 v16, v4, v7, s[2:3]
	v_cndmask_b32_e64 v17, v5, v6, s[2:3]
	s_waitcnt lgkmcnt(1)
	v_mul_f32_e32 v52, v17, v12
	v_mul_f32_e32 v53, v16, v13
	v_cndmask_b32_e64 v16, v16, v53, s[4:5]
	v_cndmask_b32_e64 v17, v17, v52, s[4:5]
	v_pk_mul_f32 v[8:9], v[8:9], v[10:11]
	ds_read2st64_b64 v[4:7], v21 offset0:11 offset1:12
	v_mul_f32_e32 v52, v17, v14
	v_mul_f32_e32 v53, v16, v15
	v_pk_mul_f32 v[8:9], v[8:9], v[12:13]
	v_cndmask_b32_e64 v16, v16, v53, s[8:9]
	v_cndmask_b32_e64 v17, v17, v52, s[8:9]
	v_pk_mul_f32 v[52:53], v[8:9], v[14:15]
	ds_read2st64_b64 v[8:11], v21 offset0:4 offset1:5
	s_waitcnt lgkmcnt(2)
	v_cndmask_b32_e64 v18, 1.0, v1, s[0:1]
	v_cndmask_b32_e64 v19, 1.0, v0, s[0:1]
	v_mul_f32_e32 v19, v19, v2
	v_mul_f32_e32 v18, v18, v3
	v_cndmask_b32_e64 v18, 1.0, v18, s[6:7]
	v_cndmask_b32_e64 v19, 1.0, v19, s[6:7]
	s_waitcnt lgkmcnt(1)
	v_mul_f32_e32 v12, v19, v4
	v_mul_f32_e32 v13, v18, v5
	v_cndmask_b32_e64 v18, 1.0, v13, s[10:11]
	v_cndmask_b32_e64 v19, 1.0, v12, s[10:11]
	ds_read2st64_b64 v[12:15], v21 offset0:6 offset1:7
	s_waitcnt lgkmcnt(1)
	v_mul_f32_e32 v66, v17, v8
	v_mul_f32_e32 v67, v16, v9
	v_cndmask_b32_e64 v67, v16, v67, s[12:13]
	v_cndmask_b32_e64 v66, v17, v66, s[12:13]
	v_mul_f32_e32 v16, v19, v6
	v_mul_f32_e32 v17, v18, v7
	v_cndmask_b32_e64 v68, 1.0, v17, s[14:15]
	v_cndmask_b32_e64 v69, 1.0, v16, s[14:15]
	ds_read2st64_b64 v[16:19], v21 offset0:13 offset1:14
	v_mul_f32_e32 v70, v66, v10
	v_mul_f32_e32 v71, v67, v11
	v_cndmask_b32_e64 v67, v67, v71, s[16:17]
	v_cndmask_b32_e64 v66, v66, v70, s[16:17]
	ds_read_b64 v[70:71], v21 offset:7680
	s_waitcnt lgkmcnt(1)
	v_mul_f32_e32 v69, v69, v16
	v_mul_f32_e32 v68, v68, v17
	v_cndmask_b32_e64 v68, 1.0, v68, s[18:19]
	v_cndmask_b32_e64 v69, 1.0, v69, s[18:19]
	v_mul_f32_e32 v74, v66, v12
	v_mul_f32_e32 v75, v67, v13
	v_cndmask_b32_e64 v67, v67, v75, s[20:21]
	v_cndmask_b32_e64 v66, v66, v74, s[20:21]
	v_mul_f32_e32 v69, v69, v18
	v_mul_f32_e32 v68, v68, v19
	v_cndmask_b32_e64 v68, 1.0, v68, s[22:23]
	v_cndmask_b32_e64 v69, 1.0, v69, s[22:23]
	v_mul_f32_e32 v74, v66, v14
	v_mul_f32_e32 v75, v67, v15
	v_cndmask_b32_e64 v114, v67, v75, s[24:25]
	v_cndmask_b32_e64 v115, v66, v74, s[24:25]
	s_waitcnt lgkmcnt(0)
	v_mul_f32_e32 v66, v69, v70
	v_mul_f32_e32 v67, v68, v71
	v_cndmask_b32_e64 v116, 1.0, v67, s[26:27]
	v_cndmask_b32_e64 v117, 1.0, v66, s[26:27]
	v_pk_mul_f32 v[66:67], v[6:7], v[16:17]
	v_rcp_f32_e32 v74, v52
	v_pk_mul_f32 v[66:67], v[66:67], v[18:19]
	v_rcp_f32_e32 v75, v53
	v_pk_mul_f32 v[68:69], v[66:67], v[70:71]
	v_mul_f32_e32 v115, v74, v115
	v_rcp_f32_e32 v66, v68
	v_rcp_f32_e32 v67, v69
	v_mul_f32_e32 v114, v75, v114
	v_mul_f32_e32 v119, v86, v115
	v_mul_f32_e32 v117, v66, v117
	v_mul_f32_e32 v116, v67, v116
	v_mul_f32_e32 v120, v87, v114
	v_mul_f32_e32 v121, v110, v117
	v_mul_f32_e32 v122, v111, v116
	v_rcp_f32_e32 v110, v119
	v_rcp_f32_e32 v111, v120
	v_mul_f32_e32 v123, v119, v118
	v_mul_f32_e32 v124, v120, v112
	v_cvt_pk_bf16_f32 v119, v123, v124
	global_store_dword v[34:35], v119, off
	v_pk_add_f32 v[34:35], v[86:87], 1.0 op_sel_hi:[1,0] neg_lo:[1,0] neg_hi:[1,0]
	v_and_b32_e32 v87, 0xffff0000, v113
	v_pk_mul_f32 v[34:35], v[34:35], v[110:111]
	v_pk_add_f32 v[28:29], v[28:29], 1.0 op_sel_hi:[1,0] neg_lo:[1,0] neg_hi:[1,0]
	v_cvt_pk_bf16_f32 v34, v34, v35
	global_store_dword v[32:33], v34, off
	v_mul_f32_e32 v32, v121, v118
	v_mul_f32_e32 v33, v122, v112
	v_cvt_pk_bf16_f32 v86, v32, v33
	v_rcp_f32_e32 v32, v121
	v_rcp_f32_e32 v33, v122
	v_lshl_add_u64 v[34:35], s[40:41], 0, v[26:27]
	global_store_dword v[34:35], v86, off
	v_pk_add_f32 v[34:35], v[108:109], 1.0 op_sel_hi:[1,0] neg_lo:[1,0] neg_hi:[1,0]
	v_lshlrev_b32_e32 v86, 16, v113
	v_pk_mul_f32 v[32:33], v[34:35], v[32:33]
	s_nop 0
	v_cvt_pk_bf16_f32 v32, v32, v33
	global_store_dword v[30:31], v32, off
	v_mul_f32_e32 v32, v82, v115
	v_mul_f32_e32 v33, v83, v114
	v_mul_f32_e32 v30, v32, v86
	v_mul_f32_e32 v31, v33, v87
	v_rcp_f32_e32 v32, v32
	v_rcp_f32_e32 v33, v33
	v_mul_f32_e32 v82, v106, v117
	v_cvt_pk_bf16_f32 v106, v30, v31
	v_or_b32_e32 v30, 0x800, v26
	v_mov_b32_e32 v31, v27
	v_lshl_add_u64 v[34:35], s[34:35], 0, v[30:31]
	global_store_dword v[34:35], v106, off
	v_pk_add_f32 v[34:35], v[78:79], 1.0 op_sel_hi:[1,0] neg_lo:[1,0] neg_hi:[1,0]
	v_mul_f32_e32 v83, v107, v116
	v_pk_mul_f32 v[32:33], v[34:35], v[32:33]
	v_and_b32_e32 v79, 0xffff0000, v101
	v_cvt_pk_bf16_f32 v34, v32, v33
	v_lshl_add_u64 v[32:33], s[36:37], 0, v[30:31]
	global_store_dword v[32:33], v34, off
	v_mul_f32_e32 v32, v82, v86
	v_mul_f32_e32 v33, v83, v87
	v_cvt_pk_bf16_f32 v78, v32, v33
	v_rcp_f32_e32 v32, v82
	v_rcp_f32_e32 v33, v83
	v_lshl_add_u64 v[34:35], s[40:41], 0, v[30:31]
	global_store_dword v[34:35], v78, off
	v_pk_add_f32 v[34:35], v[104:105], 1.0 op_sel_hi:[1,0] neg_lo:[1,0] neg_hi:[1,0]
	v_lshl_add_u64 v[30:31], s[38:39], 0, v[30:31]
	v_pk_mul_f32 v[32:33], v[34:35], v[32:33]
	v_lshlrev_b32_e32 v78, 16, v101
	v_cvt_pk_bf16_f32 v32, v32, v33
	global_store_dword v[30:31], v32, off
	v_mul_f32_e32 v32, v72, v115
	v_mul_f32_e32 v33, v73, v114
	v_mul_f32_e32 v30, v32, v78
	v_mul_f32_e32 v31, v33, v79
	v_rcp_f32_e32 v32, v32
	v_rcp_f32_e32 v33, v33
	v_cvt_pk_bf16_f32 v82, v30, v31
	v_or_b32_e32 v30, 0x1000, v26
	v_mov_b32_e32 v31, v27
	v_lshl_add_u64 v[34:35], s[34:35], 0, v[30:31]
	global_store_dword v[34:35], v82, off
	v_pk_add_f32 v[34:35], v[64:65], 1.0 op_sel_hi:[1,0] neg_lo:[1,0] neg_hi:[1,0]
	v_mul_f32_e32 v72, v102, v117
	v_pk_mul_f32 v[32:33], v[34:35], v[32:33]
	v_mul_f32_e32 v73, v103, v116
	v_cvt_pk_bf16_f32 v34, v32, v33
	v_lshl_add_u64 v[32:33], s[36:37], 0, v[30:31]
	global_store_dword v[32:33], v34, off
	v_mul_f32_e32 v32, v72, v78
	v_mul_f32_e32 v33, v73, v79
	v_cvt_pk_bf16_f32 v64, v32, v33
	v_rcp_f32_e32 v32, v72
	v_rcp_f32_e32 v33, v73
	v_lshl_add_u64 v[34:35], s[40:41], 0, v[30:31]
	global_store_dword v[34:35], v64, off
	v_pk_add_f32 v[34:35], v[92:93], 1.0 op_sel_hi:[1,0] neg_lo:[1,0] neg_hi:[1,0]
	v_lshl_add_u64 v[30:31], s[38:39], 0, v[30:31]
	v_pk_mul_f32 v[32:33], v[34:35], v[32:33]
	v_lshlrev_b32_e32 v64, 16, v99
	v_cvt_pk_bf16_f32 v32, v32, v33
	global_store_dword v[30:31], v32, off
	v_and_b32_e32 v65, 0xffff0000, v99
	v_mul_f32_e32 v32, v58, v115
	v_mul_f32_e32 v33, v59, v114
	v_mul_f32_e32 v30, v32, v64
	v_mul_f32_e32 v31, v33, v65
	v_rcp_f32_e32 v32, v32
	v_rcp_f32_e32 v33, v33
	v_cvt_pk_bf16_f32 v72, v30, v31
	v_or_b32_e32 v30, 0x1800, v26
	v_mov_b32_e32 v31, v27
	v_lshl_add_u64 v[34:35], s[34:35], 0, v[30:31]
	global_store_dword v[34:35], v72, off
	v_pk_add_f32 v[34:35], v[56:57], 1.0 op_sel_hi:[1,0] neg_lo:[1,0] neg_hi:[1,0]
	v_mul_f32_e32 v58, v90, v117
	v_pk_mul_f32 v[32:33], v[34:35], v[32:33]
	v_mul_f32_e32 v59, v91, v116
	v_cvt_pk_bf16_f32 v34, v32, v33
	v_lshl_add_u64 v[32:33], s[36:37], 0, v[30:31]
	global_store_dword v[32:33], v34, off
	v_mul_f32_e32 v32, v58, v64
	v_mul_f32_e32 v33, v59, v65
	v_cvt_pk_bf16_f32 v56, v32, v33
	v_rcp_f32_e32 v32, v58
	v_rcp_f32_e32 v33, v59
	v_lshl_add_u64 v[34:35], s[40:41], 0, v[30:31]
	global_store_dword v[34:35], v56, off
	v_pk_add_f32 v[34:35], v[88:89], 1.0 op_sel_hi:[1,0] neg_lo:[1,0] neg_hi:[1,0]
	v_lshl_add_u64 v[30:31], s[38:39], 0, v[30:31]
	v_pk_mul_f32 v[32:33], v[34:35], v[32:33]
	v_lshlrev_b32_e32 v56, 16, v100
	v_cvt_pk_bf16_f32 v32, v32, v33
	global_store_dword v[30:31], v32, off
	v_and_b32_e32 v57, 0xffff0000, v100
	v_mul_f32_e32 v32, v50, v115
	v_mul_f32_e32 v33, v51, v114
	v_mul_f32_e32 v30, v32, v56
	v_mul_f32_e32 v31, v33, v57
	v_rcp_f32_e32 v32, v32
	v_rcp_f32_e32 v33, v33
	v_cvt_pk_bf16_f32 v58, v30, v31
	v_or_b32_e32 v30, 0x2000, v26
	v_mov_b32_e32 v31, v27
	v_lshl_add_u64 v[34:35], s[34:35], 0, v[30:31]
	global_store_dword v[34:35], v58, off
	v_pk_add_f32 v[34:35], v[48:49], 1.0 op_sel_hi:[1,0] neg_lo:[1,0] neg_hi:[1,0]
	v_mul_f32_e32 v50, v84, v117
	v_pk_mul_f32 v[32:33], v[34:35], v[32:33]
	v_mul_f32_e32 v51, v85, v116
	v_cvt_pk_bf16_f32 v34, v32, v33
	v_lshl_add_u64 v[32:33], s[36:37], 0, v[30:31]
	global_store_dword v[32:33], v34, off
	v_mul_f32_e32 v32, v50, v56
	v_mul_f32_e32 v33, v51, v57
	v_cvt_pk_bf16_f32 v48, v32, v33
	v_rcp_f32_e32 v32, v50
	v_rcp_f32_e32 v33, v51
	v_lshl_add_u64 v[34:35], s[40:41], 0, v[30:31]
	global_store_dword v[34:35], v48, off
	v_pk_add_f32 v[34:35], v[80:81], 1.0 op_sel_hi:[1,0] neg_lo:[1,0] neg_hi:[1,0]
	v_lshl_add_u64 v[30:31], s[38:39], 0, v[30:31]
	v_pk_mul_f32 v[32:33], v[34:35], v[32:33]
	v_lshlrev_b32_e32 v48, 16, v98
	v_cvt_pk_bf16_f32 v32, v32, v33
	global_store_dword v[30:31], v32, off
	v_and_b32_e32 v49, 0xffff0000, v98
	v_mul_f32_e32 v32, v44, v115
	v_mul_f32_e32 v33, v45, v114
	v_mul_f32_e32 v30, v32, v48
	v_mul_f32_e32 v31, v33, v49
	v_rcp_f32_e32 v32, v32
	v_rcp_f32_e32 v33, v33
	v_cvt_pk_bf16_f32 v50, v30, v31
	v_or_b32_e32 v30, 0x2800, v26
	v_mov_b32_e32 v31, v27
	v_lshl_add_u64 v[34:35], s[34:35], 0, v[30:31]
	global_store_dword v[34:35], v50, off
	v_pk_add_f32 v[34:35], v[42:43], 1.0 op_sel_hi:[1,0] neg_lo:[1,0] neg_hi:[1,0]
	v_mul_f32_e32 v44, v76, v117
	v_pk_mul_f32 v[32:33], v[34:35], v[32:33]
	v_mul_f32_e32 v45, v77, v116
	v_cvt_pk_bf16_f32 v34, v32, v33
	v_lshl_add_u64 v[32:33], s[36:37], 0, v[30:31]
	global_store_dword v[32:33], v34, off
	v_mul_f32_e32 v32, v44, v48
	v_mul_f32_e32 v33, v45, v49
	v_cvt_pk_bf16_f32 v42, v32, v33
	v_rcp_f32_e32 v32, v44
	v_rcp_f32_e32 v33, v45
	v_lshl_add_u64 v[34:35], s[40:41], 0, v[30:31]
	global_store_dword v[34:35], v42, off
	v_pk_add_f32 v[34:35], v[62:63], 1.0 op_sel_hi:[1,0] neg_lo:[1,0] neg_hi:[1,0]
	v_lshl_add_u64 v[30:31], s[38:39], 0, v[30:31]
	v_pk_mul_f32 v[32:33], v[34:35], v[32:33]
	s_waitcnt vmcnt(24)
	v_lshlrev_b32_e32 v42, 16, v97
	v_cvt_pk_bf16_f32 v32, v32, v33
	global_store_dword v[30:31], v32, off
	v_and_b32_e32 v43, 0xffff0000, v97
	v_mul_f32_e32 v32, v40, v115
	v_mul_f32_e32 v33, v41, v114
	v_mul_f32_e32 v30, v32, v42
	v_mul_f32_e32 v31, v33, v43
	v_rcp_f32_e32 v32, v32
	v_rcp_f32_e32 v33, v33
	v_cvt_pk_bf16_f32 v44, v30, v31
	v_or_b32_e32 v30, 0x3000, v26
	v_mov_b32_e32 v31, v27
	v_lshl_add_u64 v[34:35], s[34:35], 0, v[30:31]
	global_store_dword v[34:35], v44, off
	v_pk_add_f32 v[34:35], v[38:39], 1.0 op_sel_hi:[1,0] neg_lo:[1,0] neg_hi:[1,0]
	v_mul_f32_e32 v40, v60, v117
	v_pk_mul_f32 v[32:33], v[34:35], v[32:33]
	v_mul_f32_e32 v41, v61, v116
	v_cvt_pk_bf16_f32 v34, v32, v33
	v_lshl_add_u64 v[32:33], s[36:37], 0, v[30:31]
	global_store_dword v[32:33], v34, off
	v_mul_f32_e32 v32, v40, v42
	v_mul_f32_e32 v33, v41, v43
	v_cvt_pk_bf16_f32 v38, v32, v33
	v_rcp_f32_e32 v32, v40
	v_rcp_f32_e32 v33, v41
	v_lshl_add_u64 v[34:35], s[40:41], 0, v[30:31]
	global_store_dword v[34:35], v38, off
	v_pk_add_f32 v[34:35], v[54:55], 1.0 op_sel_hi:[1,0] neg_lo:[1,0] neg_hi:[1,0]
	v_lshl_add_u64 v[30:31], s[38:39], 0, v[30:31]
	v_pk_mul_f32 v[32:33], v[34:35], v[32:33]
	s_waitcnt vmcnt(27)
	v_lshlrev_b32_e32 v34, 16, v22
	v_cvt_pk_bf16_f32 v32, v32, v33
	global_store_dword v[30:31], v32, off
	v_and_b32_e32 v22, 0xffff0000, v22
	v_mul_f32_e32 v30, v36, v115
	v_mul_f32_e32 v31, v37, v114
	v_mul_f32_e32 v32, v30, v34
	v_mul_f32_e32 v33, v31, v22
	v_rcp_f32_e32 v30, v30
	v_rcp_f32_e32 v31, v31
	v_or_b32_e32 v26, 0x3800, v26
	v_mul_f32_e32 v35, v46, v117
	v_mul_f32_e32 v36, v47, v116
	v_pk_mul_f32 v[28:29], v[28:29], v[30:31]
	v_mul_f32_e32 v22, v36, v22
	v_cvt_pk_bf16_f32 v30, v28, v29
	v_lshl_add_u64 v[28:29], s[36:37], 0, v[26:27]
	global_store_dword v[28:29], v30, off
	v_mul_f32_e32 v28, v35, v34
	v_cvt_pk_bf16_f32 v22, v28, v22
	v_rcp_f32_e32 v28, v35
	v_rcp_f32_e32 v29, v36
	v_lshl_add_u64 v[30:31], s[40:41], 0, v[26:27]
	global_store_dword v[30:31], v22, off
	v_pk_add_f32 v[30:31], v[46:47], 1.0 op_sel_hi:[1,0] neg_lo:[1,0] neg_hi:[1,0]
	v_cvt_pk_bf16_f32 v37, v32, v33
	v_pk_mul_f32 v[28:29], v[30:31], v[28:29]
	v_lshl_add_u64 v[32:33], s[34:35], 0, v[26:27]
	v_cvt_pk_bf16_f32 v22, v28, v29
	v_lshl_add_u64 v[26:27], s[38:39], 0, v[26:27]
	global_store_dword v[32:33], v37, off
	global_store_dword v[26:27], v22, off
	s_and_saveexec_b64 s[44:45], s[0:1]
	s_cbranch_execz .LBB0_551
	ds_read_b64 v[26:27], v21 offset:4096
	s_lshl_b32 s42, s42, 3
	v_pk_mul_f32 v[8:9], v[52:53], v[8:9]
	s_or_b32 s42, s42, s50
	v_pk_mul_f32 v[8:9], v[8:9], v[10:11]
	s_waitcnt lgkmcnt(0)
	v_pk_mul_f32 v[0:1], v[26:27], v[0:1]
	s_lshl_b32 s43, s42, 7
	v_pk_mul_f32 v[0:1], v[0:1], v[2:3]
	s_add_i32 s42, s42, 32
	v_pk_mul_f32 v[8:9], v[8:9], v[12:13]
	v_pk_mul_f32 v[0:1], v[0:1], v[4:5]
	s_or_b32 s50, s43, s49
	s_ashr_i32 s43, s42, 31
	v_pk_mul_f32 v[8:9], v[8:9], v[14:15]
	v_pk_mul_f32 v[0:1], v[0:1], v[6:7]
	s_lshl_b64 s[42:43], s[42:43], 7
	s_xor_b32 s49, s49, 0x7f
	v_pk_mul_f32 v[0:1], v[0:1], v[16:17]
	s_or_b32 s42, s42, s49
	v_mad_i64_i32 v[2:3], s[50:51], s50, v96, v[24:25]
	v_pk_mul_f32 v[4:5], v[74:75], v[8:9]
	v_pk_mul_f32 v[0:1], v[0:1], v[18:19]
	global_store_dwordx2 v[2:3], v[52:53], off
	global_store_dwordx2 v[2:3], v[8:9], off offset:512
	global_store_dwordx2 v[2:3], v[4:5], off offset:1024
	s_mul_i32 s49, s43, 0x600
	v_mad_u64_u32 v[2:3], s[42:43], s42, v96, v[24:25]
	v_pk_mul_f32 v[0:1], v[0:1], v[70:71]
	v_add_u32_e32 v3, s49, v3
	global_store_dwordx2 v[2:3], v[68:69], off
	global_store_dwordx2 v[2:3], v[0:1], off offset:512
	v_pk_mul_f32 v[0:1], v[0:1], v[66:67]
	global_store_dwordx2 v[2:3], v[0:1], off offset:1024
	s_branch .LBB0_551
